# hoist agent-scope L1 invalidate of each grid barrier to start of thread-0 work (overlaps wait); late invalidates removed
# speedup vs baseline: 1.0136x; 1.0085x over previous
.LBB0_95:
	s_or_b64 exec, exec, s[2:3]
	s_waitcnt vmcnt(0)
	s_barrier
	s_mov_b64 s[0:1], exec
	v_readlane_b32 s2, v248, 48
	v_readlane_b32 s3, v248, 49
	s_and_b64 s[2:3], s[0:1], s[2:3]
	s_mov_b64 exec, s[2:3]
	s_cbranch_execz .LBB0_147
	s_add_i32 s2, 0, 0x22000
	v_mov_b32_e32 v0, s2
	s_waitcnt vmcnt(0) expcnt(0) lgkmcnt(0)
	buffer_inv sc1
	ds_read_b32 v2, v0
	s_add_i32 s2, 0, 0x22004
	v_mov_b32_e32 v0, s2
	ds_read_b32 v0, v0
	s_waitcnt lgkmcnt(1)
	v_cmp_ne_u32_e32 vcc, 0, v2
	s_cbranch_vccnz .LBB0_111
	v_readlane_b32 s2, v248, 8
	s_waitcnt lgkmcnt(0)
	v_mov_b32_e32 v0, 0
	v_readlane_b32 s3, v248, 9
	s_nop 4
	global_load_dword v1, v0, s[2:3] offset:18
	global_load_ushort v2, v0, s[2:3] offset:22
	s_mov_b32 s46, 1
	s_waitcnt vmcnt(1)
	v_cmp_ne_u32_sdwa s[2:3], v1, v0 src0_sel:WORD_0 src1_sel:DWORD
	s_cmp_lg_u64 s[2:3], 0
	v_readlane_b32 s2, v248, 10
	v_cmp_ne_u32_sdwa s[6:7], v1, v0 src0_sel:WORD_1 src1_sel:DWORD
	s_addc_u32 s2, s2, 0
	v_readlane_b32 s3, v248, 11
	s_cmp_lg_u64 s[6:7], 0
	s_waitcnt vmcnt(0)
	v_cmp_ne_u32_e32 vcc, 0, v2
	s_addc_u32 s3, s3, 0
	s_mul_i32 s33, s3, s2
	s_cmp_lg_u64 vcc, 0
	v_readlane_b32 s2, v248, 12
	s_addc_u32 s2, s2, 0
	s_mul_i32 s33, s33, s2
	s_add_u32 s2, s58, 0x3e680200
	s_addc_u32 s3, s59, 0
	s_add_u32 s6, s58, 0x3e680400
	s_addc_u32 s7, s59, 0
	s_add_u32 s8, s58, 0x3e680500
	s_addc_u32 s9, s59, 0
	s_add_u32 s10, s58, 0x3e680600
	s_addc_u32 s11, s59, 0
	s_add_u32 s12, s58, 0x3e680700
	s_addc_u32 s13, s59, 0
	s_add_u32 s14, s58, 0x3e680800
	s_addc_u32 s15, s59, 0
	s_add_u32 s16, s58, 0x3e680900
	s_addc_u32 s17, s59, 0
	s_add_u32 s18, s58, 0x3e680a00
	s_addc_u32 s19, s59, 0
	s_add_u32 s20, s58, 0x3e680b00
	s_addc_u32 s21, s59, 0
	s_add_u32 s22, s58, 0x3e680c00
	s_addc_u32 s23, s59, 0
	s_add_u32 s24, s58, 0x3e680d00
	s_addc_u32 s25, s59, 0
	s_add_u32 s26, s58, 0x3e680e00
	s_addc_u32 s27, s59, 0
	s_add_u32 s28, s58, 0x3e680f00
	s_addc_u32 s29, s59, 0
	s_add_u32 s30, s58, 0x3e681000
	s_addc_u32 s31, s59, 0
	s_add_u32 s34, s58, 0x3e681100
	s_addc_u32 s35, s59, 0
	s_add_u32 s36, s58, 0x3e681200
	s_addc_u32 s37, s59, 0
	s_add_u32 s38, s58, 0x3e681300
	s_addc_u32 s39, s59, 0
	s_branch .LBB0_99

.LBB0_126:
	s_or_b64 exec, exec, s[8:9]
	s_waitcnt vmcnt(0)
	s_waitcnt vmcnt(0)

.LBB0_144:
	s_or_b64 exec, exec, s[6:7]
	s_mov_b64 s[6:7], exec
	v_mbcnt_lo_u32_b32 v0, s6, 0
	v_mbcnt_hi_u32_b32 v0, s7, v0
	v_cmp_eq_u32_e32 vcc, 0, v0
	s_waitcnt vmcnt(0)
	s_and_saveexec_b64 s[8:9], vcc
	s_cbranch_execz .LBB0_146
	s_bcnt1_i32_b64 s6, s[6:7]
	v_mov_b32_e32 v0, 0x2000
	v_mov_b32_e32 v1, s6
	global_atomic_add v0, v1, s[2:3] offset:1024

.LBB0_201:
	s_waitcnt vmcnt(0)
	s_waitcnt vmcnt(0) lgkmcnt(0)
	s_barrier
	s_mov_b64 s[0:1], exec
	v_readlane_b32 s2, v248, 48
	v_readlane_b32 s3, v248, 49
	s_and_b64 s[2:3], s[0:1], s[2:3]
	s_mov_b64 exec, s[2:3]
	s_cbranch_execz .LBB0_253
	s_add_i32 s2, 0, 0x22000
	v_mov_b32_e32 v0, s2
	s_waitcnt vmcnt(0) expcnt(0) lgkmcnt(0)
	buffer_inv sc1
	ds_read_b32 v2, v0
	s_add_i32 s2, 0, 0x22004
	v_mov_b32_e32 v0, s2
	ds_read_b32 v0, v0
	s_waitcnt lgkmcnt(1)
	v_cmp_ne_u32_e32 vcc, 0, v2
	s_cbranch_vccnz .LBB0_217
	v_readlane_b32 s2, v248, 8
	s_waitcnt lgkmcnt(0)
	v_mov_b32_e32 v0, 0
	v_readlane_b32 s3, v248, 9
	s_nop 4
	global_load_dword v1, v0, s[2:3] offset:18
	global_load_ushort v2, v0, s[2:3] offset:22
	s_mov_b32 s46, 1
	s_waitcnt vmcnt(1)
	v_cmp_ne_u32_sdwa s[2:3], v1, v0 src0_sel:WORD_0 src1_sel:DWORD
	s_cmp_lg_u64 s[2:3], 0
	v_readlane_b32 s2, v248, 10
	v_cmp_ne_u32_sdwa s[4:5], v1, v0 src0_sel:WORD_1 src1_sel:DWORD
	s_addc_u32 s2, s2, 0
	v_readlane_b32 s3, v248, 11
	s_cmp_lg_u64 s[4:5], 0
	s_waitcnt vmcnt(0)
	v_cmp_ne_u32_e32 vcc, 0, v2
	s_addc_u32 s3, s3, 0
	s_mul_i32 s33, s3, s2
	s_cmp_lg_u64 vcc, 0
	v_readlane_b32 s2, v248, 12
	s_addc_u32 s2, s2, 0
	s_mul_i32 s33, s33, s2
	s_add_u32 s2, s58, 0x3e680200
	s_addc_u32 s3, s59, 0
	s_add_u32 s4, s58, 0x3e680400
	s_addc_u32 s5, s59, 0
	s_add_u32 s6, s58, 0x3e680500
	s_addc_u32 s7, s59, 0
	s_add_u32 s8, s58, 0x3e680600
	s_addc_u32 s9, s59, 0
	s_add_u32 s10, s58, 0x3e680700
	s_addc_u32 s11, s59, 0
	s_add_u32 s14, s58, 0x3e680800
	s_addc_u32 s15, s59, 0
	s_add_u32 s16, s58, 0x3e680900
	s_addc_u32 s17, s59, 0
	s_add_u32 s18, s58, 0x3e680a00
	s_addc_u32 s19, s59, 0
	s_add_u32 s20, s58, 0x3e680b00
	s_addc_u32 s21, s59, 0
	s_add_u32 s22, s58, 0x3e680c00
	s_addc_u32 s23, s59, 0
	s_add_u32 s24, s58, 0x3e680d00
	s_addc_u32 s25, s59, 0
	s_add_u32 s26, s58, 0x3e680e00
	s_addc_u32 s27, s59, 0
	s_add_u32 s28, s58, 0x3e680f00
	s_addc_u32 s29, s59, 0
	s_add_u32 s30, s58, 0x3e681000
	s_addc_u32 s31, s59, 0
	s_add_u32 s34, s58, 0x3e681100
	s_addc_u32 s35, s59, 0
	s_add_u32 s36, s58, 0x3e681200
	s_addc_u32 s37, s59, 0
	s_add_u32 s38, s58, 0x3e681300
	s_addc_u32 s39, s59, 0
	s_branch .LBB0_205

.LBB0_232:
	s_or_b64 exec, exec, s[6:7]
	s_waitcnt vmcnt(0)
	s_waitcnt vmcnt(0)

.LBB0_250:
	s_or_b64 exec, exec, s[4:5]
	s_mov_b64 s[4:5], exec
	v_mbcnt_lo_u32_b32 v0, s4, 0
	v_mbcnt_hi_u32_b32 v0, s5, v0
	v_cmp_eq_u32_e32 vcc, 0, v0
	s_waitcnt vmcnt(0)
	s_and_saveexec_b64 s[6:7], vcc
	s_cbranch_execz .LBB0_252
	s_bcnt1_i32_b64 s4, s[4:5]
	v_mov_b32_e32 v0, 0x2000
	v_mov_b32_e32 v1, s4
	global_atomic_add v0, v1, s[2:3] offset:1024

.LBB0_306:
	s_or_b64 exec, exec, s[16:17]
	s_waitcnt vmcnt(0)
	s_barrier
	s_mov_b64 s[0:1], exec
	v_readlane_b32 s2, v248, 48
	v_readlane_b32 s3, v248, 49
	s_and_b64 s[2:3], s[0:1], s[2:3]
	s_mov_b64 exec, s[2:3]
	s_cbranch_execz .LBB0_358
	s_add_i32 s2, 0, 0x22000
	v_mov_b32_e32 v0, s2
	s_waitcnt vmcnt(0) expcnt(0) lgkmcnt(0)
	buffer_inv sc1
	ds_read_b32 v2, v0
	s_add_i32 s2, 0, 0x22004
	v_mov_b32_e32 v0, s2
	ds_read_b32 v0, v0
	s_waitcnt lgkmcnt(1)
	v_cmp_ne_u32_e32 vcc, 0, v2
	s_cbranch_vccnz .LBB0_322
	v_readlane_b32 s2, v248, 8
	s_waitcnt lgkmcnt(0)
	v_mov_b32_e32 v0, 0
	v_readlane_b32 s3, v248, 9
	s_nop 4
	global_load_dword v1, v0, s[2:3] offset:18
	global_load_ushort v2, v0, s[2:3] offset:22
	s_mov_b32 s50, 1
	s_waitcnt vmcnt(1)
	v_cmp_ne_u32_sdwa s[2:3], v1, v0 src0_sel:WORD_0 src1_sel:DWORD
	s_cmp_lg_u64 s[2:3], 0
	v_readlane_b32 s2, v248, 10
	v_cmp_ne_u32_sdwa s[4:5], v1, v0 src0_sel:WORD_1 src1_sel:DWORD
	s_addc_u32 s2, s2, 0
	v_readlane_b32 s3, v248, 11
	s_cmp_lg_u64 s[4:5], 0
	s_waitcnt vmcnt(0)
	v_cmp_ne_u32_e32 vcc, 0, v2
	s_addc_u32 s3, s3, 0
	s_mul_i32 s33, s3, s2
	s_cmp_lg_u64 vcc, 0
	v_readlane_b32 s2, v248, 12
	s_addc_u32 s2, s2, 0
	s_mul_i32 s33, s33, s2
	s_add_u32 s2, s58, 0x3e680200
	s_addc_u32 s3, s59, 0
	s_add_u32 s4, s58, 0x3e680400
	s_addc_u32 s5, s59, 0
	s_add_u32 s6, s58, 0x3e680500
	s_addc_u32 s7, s59, 0
	s_add_u32 s8, s58, 0x3e680600
	s_addc_u32 s9, s59, 0
	s_add_u32 s16, s58, 0x3e680700
	s_addc_u32 s17, s59, 0
	s_add_u32 s18, s58, 0x3e680800
	s_addc_u32 s19, s59, 0
	s_add_u32 s20, s58, 0x3e680900
	s_addc_u32 s21, s59, 0
	s_add_u32 s22, s58, 0x3e680a00
	s_addc_u32 s23, s59, 0
	s_add_u32 s24, s58, 0x3e680b00
	s_addc_u32 s25, s59, 0
	s_add_u32 s26, s58, 0x3e680c00
	s_addc_u32 s27, s59, 0
	s_add_u32 s28, s58, 0x3e680d00
	s_addc_u32 s29, s59, 0
	s_add_u32 s30, s58, 0x3e680e00
	s_addc_u32 s31, s59, 0
	s_add_u32 s34, s58, 0x3e680f00
	s_addc_u32 s35, s59, 0
	s_add_u32 s36, s58, 0x3e681000
	s_addc_u32 s37, s59, 0
	s_add_u32 s38, s58, 0x3e681100
	s_addc_u32 s39, s59, 0
	s_add_u32 s40, s58, 0x3e681200
	s_addc_u32 s41, s59, 0
	s_add_u32 s42, s58, 0x3e681300
	s_addc_u32 s43, s59, 0
	s_branch .LBB0_310

.LBB0_372:
	s_waitcnt vmcnt(0)
	s_waitcnt vmcnt(0) lgkmcnt(0)
	s_barrier
	s_mov_b64 s[0:1], exec
	v_readlane_b32 s2, v248, 48
	v_readlane_b32 s3, v248, 49
	s_and_b64 s[2:3], s[0:1], s[2:3]
	s_mov_b64 exec, s[2:3]
	s_cbranch_execz .LBB0_424
	s_add_i32 s2, 0, 0x22000
	v_mov_b32_e32 v0, s2
	s_waitcnt vmcnt(0) expcnt(0) lgkmcnt(0)
	buffer_inv sc1
	ds_read_b32 v2, v0
	s_add_i32 s2, 0, 0x22004
	v_mov_b32_e32 v0, s2
	ds_read_b32 v0, v0
	s_waitcnt lgkmcnt(1)
	v_cmp_ne_u32_e32 vcc, 0, v2
	s_cbranch_vccnz .LBB0_388
	v_readlane_b32 s2, v248, 8
	s_waitcnt lgkmcnt(0)
	v_mov_b32_e32 v0, 0
	v_readlane_b32 s3, v248, 9
	s_nop 4
	global_load_dword v1, v0, s[2:3] offset:18
	global_load_ushort v2, v0, s[2:3] offset:22
	s_mov_b32 s50, 1
	s_waitcnt vmcnt(1)
	v_cmp_ne_u32_sdwa s[2:3], v1, v0 src0_sel:WORD_0 src1_sel:DWORD
	s_cmp_lg_u64 s[2:3], 0
	v_readlane_b32 s2, v248, 10
	v_cmp_ne_u32_sdwa s[6:7], v1, v0 src0_sel:WORD_1 src1_sel:DWORD
	s_addc_u32 s2, s2, 0
	v_readlane_b32 s3, v248, 11
	s_cmp_lg_u64 s[6:7], 0
	s_waitcnt vmcnt(0)
	v_cmp_ne_u32_e32 vcc, 0, v2
	s_addc_u32 s3, s3, 0
	s_mul_i32 s33, s3, s2
	s_cmp_lg_u64 vcc, 0
	v_readlane_b32 s2, v248, 12
	s_addc_u32 s2, s2, 0
	s_mul_i32 s33, s33, s2
	s_add_u32 s2, s58, 0x3e680200
	s_addc_u32 s3, s59, 0
	s_add_u32 s6, s58, 0x3e680400
	s_addc_u32 s7, s59, 0
	s_add_u32 s8, s58, 0x3e680500
	s_addc_u32 s9, s59, 0
	s_add_u32 s14, s58, 0x3e680600
	s_addc_u32 s15, s59, 0
	s_add_u32 s16, s58, 0x3e680700
	s_addc_u32 s17, s59, 0
	s_add_u32 s18, s58, 0x3e680800
	s_addc_u32 s19, s59, 0
	s_add_u32 s20, s58, 0x3e680900
	s_addc_u32 s21, s59, 0
	s_add_u32 s22, s58, 0x3e680a00
	s_addc_u32 s23, s59, 0
	s_add_u32 s24, s58, 0x3e680b00
	s_addc_u32 s25, s59, 0
	s_add_u32 s26, s58, 0x3e680c00
	s_addc_u32 s27, s59, 0
	s_add_u32 s28, s58, 0x3e680d00
	s_addc_u32 s29, s59, 0
	s_add_u32 s30, s58, 0x3e680e00
	s_addc_u32 s31, s59, 0
	s_add_u32 s34, s58, 0x3e680f00
	s_addc_u32 s35, s59, 0
	s_add_u32 s36, s58, 0x3e681000
	s_addc_u32 s37, s59, 0
	s_add_u32 s38, s58, 0x3e681100
	s_addc_u32 s39, s59, 0
	s_add_u32 s40, s58, 0x3e681200
	s_addc_u32 s41, s59, 0
	s_add_u32 s42, s58, 0x3e681300
	s_addc_u32 s43, s59, 0
	s_branch .LBB0_376

.LBB0_472:
	s_or_b64 exec, exec, s[2:3]
	s_waitcnt vmcnt(0)
	s_barrier
	s_mov_b64 s[0:1], exec
	v_readlane_b32 s2, v248, 48
	v_readlane_b32 s3, v248, 49
	s_and_b64 s[2:3], s[0:1], s[2:3]
	s_mov_b64 exec, s[2:3]
	s_cbranch_execz .LBB0_524
	s_add_i32 s2, 0, 0x22000
	v_mov_b32_e32 v0, s2
	s_waitcnt vmcnt(0) expcnt(0) lgkmcnt(0)
	buffer_inv sc1
	ds_read_b32 v2, v0
	s_add_i32 s2, 0, 0x22004
	v_mov_b32_e32 v0, s2
	ds_read_b32 v0, v0
	s_waitcnt lgkmcnt(1)
	v_cmp_ne_u32_e32 vcc, 0, v2
	s_cbranch_vccnz .LBB0_488
	v_readlane_b32 s2, v248, 8
	s_waitcnt lgkmcnt(0)
	v_mov_b32_e32 v0, 0
	v_readlane_b32 s3, v248, 9
	s_nop 4
	global_load_dword v1, v0, s[2:3] offset:18
	global_load_ushort v2, v0, s[2:3] offset:22
	s_mov_b32 s50, 1
	s_waitcnt vmcnt(1)
	v_cmp_ne_u32_sdwa s[2:3], v1, v0 src0_sel:WORD_0 src1_sel:DWORD
	s_cmp_lg_u64 s[2:3], 0
	v_readlane_b32 s2, v248, 10
	v_cmp_ne_u32_sdwa s[6:7], v1, v0 src0_sel:WORD_1 src1_sel:DWORD
	s_addc_u32 s2, s2, 0
	v_readlane_b32 s3, v248, 11
	s_cmp_lg_u64 s[6:7], 0
	s_waitcnt vmcnt(0)
	v_cmp_ne_u32_e32 vcc, 0, v2
	s_addc_u32 s3, s3, 0
	s_mul_i32 s33, s3, s2
	s_cmp_lg_u64 vcc, 0
	v_readlane_b32 s2, v248, 12
	s_addc_u32 s2, s2, 0
	s_mul_i32 s33, s33, s2
	s_add_u32 s2, s58, 0x3e680200
	s_addc_u32 s3, s59, 0
	s_add_u32 s6, s58, 0x3e680400
	s_addc_u32 s7, s59, 0
	s_add_u32 s8, s58, 0x3e680500
	s_addc_u32 s9, s59, 0
	s_add_u32 s14, s58, 0x3e680600
	s_addc_u32 s15, s59, 0
	s_add_u32 s16, s58, 0x3e680700
	s_addc_u32 s17, s59, 0
	s_add_u32 s18, s58, 0x3e680800
	s_addc_u32 s19, s59, 0
	s_add_u32 s20, s58, 0x3e680900
	s_addc_u32 s21, s59, 0
	s_add_u32 s22, s58, 0x3e680a00
	s_addc_u32 s23, s59, 0
	s_add_u32 s24, s58, 0x3e680b00
	s_addc_u32 s25, s59, 0
	s_add_u32 s26, s58, 0x3e680c00
	s_addc_u32 s27, s59, 0
	s_add_u32 s28, s58, 0x3e680d00
	s_addc_u32 s29, s59, 0
	s_add_u32 s30, s58, 0x3e680e00
	s_addc_u32 s31, s59, 0
	s_add_u32 s34, s58, 0x3e680f00
	s_addc_u32 s35, s59, 0
	s_add_u32 s36, s58, 0x3e681000
	s_addc_u32 s37, s59, 0
	s_add_u32 s38, s58, 0x3e681100
	s_addc_u32 s39, s59, 0
	s_add_u32 s40, s58, 0x3e681200
	s_addc_u32 s41, s59, 0
	s_add_u32 s42, s58, 0x3e681300
	s_addc_u32 s43, s59, 0
	s_branch .LBB0_476

.LBB0_582:
	s_waitcnt vmcnt(0)
	s_waitcnt vmcnt(0) lgkmcnt(0)
	s_barrier
	s_mov_b64 s[0:1], exec
	v_readlane_b32 s2, v248, 48
	v_readlane_b32 s3, v248, 49
	s_and_b64 s[2:3], s[0:1], s[2:3]
	s_mov_b64 exec, s[2:3]
	s_cbranch_execz .LBB0_634
	s_add_i32 s2, 0, 0x22000
	v_mov_b32_e32 v0, s2
	s_waitcnt vmcnt(0) expcnt(0) lgkmcnt(0)
	buffer_inv sc1
	ds_read_b32 v2, v0
	s_add_i32 s2, 0, 0x22004
	v_mov_b32_e32 v0, s2
	ds_read_b32 v0, v0
	s_waitcnt lgkmcnt(1)
	v_cmp_ne_u32_e32 vcc, 0, v2
	s_cbranch_vccnz .LBB0_598
	v_readlane_b32 s2, v248, 8
	s_waitcnt lgkmcnt(0)
	v_mov_b32_e32 v0, 0
	v_readlane_b32 s3, v248, 9
	s_nop 4
	global_load_dword v1, v0, s[2:3] offset:18
	global_load_ushort v2, v0, s[2:3] offset:22
	s_mov_b32 s46, 1
	s_waitcnt vmcnt(1)
	v_cmp_ne_u32_sdwa s[2:3], v1, v0 src0_sel:WORD_0 src1_sel:DWORD
	s_cmp_lg_u64 s[2:3], 0
	v_readlane_b32 s2, v248, 10
	v_cmp_ne_u32_sdwa s[4:5], v1, v0 src0_sel:WORD_1 src1_sel:DWORD
	s_addc_u32 s2, s2, 0
	v_readlane_b32 s3, v248, 11
	s_cmp_lg_u64 s[4:5], 0
	s_waitcnt vmcnt(0)
	v_cmp_ne_u32_e32 vcc, 0, v2
	s_addc_u32 s3, s3, 0
	s_mul_i32 s33, s3, s2
	s_cmp_lg_u64 vcc, 0
	v_readlane_b32 s2, v248, 12
	s_addc_u32 s2, s2, 0
	s_mul_i32 s33, s33, s2
	s_add_u32 s2, s58, 0x3e680200
	s_addc_u32 s3, s59, 0
	s_add_u32 s4, s58, 0x3e680400
	s_addc_u32 s5, s59, 0
	s_add_u32 s6, s58, 0x3e680500
	s_addc_u32 s7, s59, 0
	s_add_u32 s8, s58, 0x3e680600
	s_addc_u32 s9, s59, 0
	s_add_u32 s12, s58, 0x3e680700
	s_addc_u32 s13, s59, 0
	s_add_u32 s14, s58, 0x3e680800
	s_addc_u32 s15, s59, 0
	s_add_u32 s16, s58, 0x3e680900
	s_addc_u32 s17, s59, 0
	s_add_u32 s18, s58, 0x3e680a00
	s_addc_u32 s19, s59, 0
	s_add_u32 s20, s58, 0x3e680b00
	s_addc_u32 s21, s59, 0
	s_add_u32 s22, s58, 0x3e680c00
	s_addc_u32 s23, s59, 0
	s_add_u32 s24, s58, 0x3e680d00
	s_addc_u32 s25, s59, 0
	s_add_u32 s26, s58, 0x3e680e00
	s_addc_u32 s27, s59, 0
	s_add_u32 s28, s58, 0x3e680f00
	s_addc_u32 s29, s59, 0
	s_add_u32 s30, s58, 0x3e681000
	s_addc_u32 s31, s59, 0
	s_add_u32 s34, s58, 0x3e681100
	s_addc_u32 s35, s59, 0
	s_add_u32 s36, s58, 0x3e681200
	s_addc_u32 s37, s59, 0
	s_add_u32 s38, s58, 0x3e681300
	s_addc_u32 s39, s59, 0
	s_branch .LBB0_586

.LBB0_648:
	s_waitcnt vmcnt(0)
	s_waitcnt vmcnt(0) lgkmcnt(0)
	s_barrier
	s_mov_b64 s[0:1], exec
	v_readlane_b32 s2, v248, 48
	v_readlane_b32 s3, v248, 49
	s_and_b64 s[2:3], s[0:1], s[2:3]
	s_mov_b64 exec, s[2:3]
	s_cbranch_execz .LBB0_700
	s_add_i32 s2, 0, 0x22000
	v_mov_b32_e32 v0, s2
	s_waitcnt vmcnt(0) expcnt(0) lgkmcnt(0)
	buffer_inv sc1
	ds_read_b32 v2, v0
	s_add_i32 s2, 0, 0x22004
	v_mov_b32_e32 v0, s2
	ds_read_b32 v0, v0
	s_waitcnt lgkmcnt(1)
	v_cmp_ne_u32_e32 vcc, 0, v2
	s_cbranch_vccnz .LBB0_664
	v_readlane_b32 s2, v248, 8
	s_waitcnt lgkmcnt(0)
	v_mov_b32_e32 v0, 0
	v_readlane_b32 s3, v248, 9
	s_nop 4
	global_load_dword v1, v0, s[2:3] offset:18
	global_load_ushort v2, v0, s[2:3] offset:22
	s_mov_b32 s47, 1
	s_waitcnt vmcnt(1)
	v_cmp_ne_u32_sdwa s[2:3], v1, v0 src0_sel:WORD_0 src1_sel:DWORD
	s_cmp_lg_u64 s[2:3], 0
	v_readlane_b32 s2, v248, 10
	v_cmp_ne_u32_sdwa s[4:5], v1, v0 src0_sel:WORD_1 src1_sel:DWORD
	s_addc_u32 s2, s2, 0
	v_readlane_b32 s3, v248, 11
	s_cmp_lg_u64 s[4:5], 0
	s_waitcnt vmcnt(0)
	v_cmp_ne_u32_e32 vcc, 0, v2
	s_addc_u32 s3, s3, 0
	s_mul_i32 s46, s3, s2
	s_cmp_lg_u64 vcc, 0
	v_readlane_b32 s2, v248, 12
	s_addc_u32 s2, s2, 0
	s_mul_i32 s46, s46, s2
	s_add_u32 s2, s58, 0x3e680200
	s_addc_u32 s3, s59, 0
	s_add_u32 s4, s58, 0x3e680400
	s_addc_u32 s5, s59, 0
	s_add_u32 s6, s58, 0x3e680500
	s_addc_u32 s7, s59, 0
	s_add_u32 s8, s58, 0x3e680600
	s_addc_u32 s9, s59, 0
	s_add_u32 s12, s58, 0x3e680700
	s_addc_u32 s13, s59, 0
	s_add_u32 s14, s58, 0x3e680800
	s_addc_u32 s15, s59, 0
	s_add_u32 s16, s58, 0x3e680900
	s_addc_u32 s17, s59, 0
	s_add_u32 s18, s58, 0x3e680a00
	s_addc_u32 s19, s59, 0
	s_add_u32 s20, s58, 0x3e680b00
	s_addc_u32 s21, s59, 0
	s_add_u32 s22, s58, 0x3e680c00
	s_addc_u32 s23, s59, 0
	s_add_u32 s24, s58, 0x3e680d00
	s_addc_u32 s25, s59, 0
	s_add_u32 s26, s58, 0x3e680e00
	s_addc_u32 s27, s59, 0
	s_add_u32 s28, s58, 0x3e680f00
	s_addc_u32 s29, s59, 0
	s_add_u32 s30, s58, 0x3e681000
	s_addc_u32 s31, s59, 0
	s_add_u32 s34, s58, 0x3e681100
	s_addc_u32 s35, s59, 0
	s_add_u32 s36, s58, 0x3e681200
	s_addc_u32 s37, s59, 0
	s_add_u32 s38, s58, 0x3e681300
	s_addc_u32 s39, s59, 0
	s_branch .LBB0_652

.LBB0_740:
	s_or_b64 exec, exec, s[2:3]
	s_waitcnt vmcnt(0)
	s_barrier
	s_mov_b64 s[0:1], exec
	v_readlane_b32 s2, v248, 48
	v_readlane_b32 s3, v248, 49
	s_and_b64 s[2:3], s[0:1], s[2:3]
	s_mov_b64 exec, s[2:3]
	s_cbranch_execz .LBB0_792
	s_add_i32 s2, 0, 0x22000
	v_mov_b32_e32 v0, s2
	s_waitcnt vmcnt(0) expcnt(0) lgkmcnt(0)
	buffer_inv sc1
	ds_read_b32 v2, v0
	s_add_i32 s2, 0, 0x22004
	v_mov_b32_e32 v0, s2
	ds_read_b32 v0, v0
	s_waitcnt lgkmcnt(1)
	v_cmp_ne_u32_e32 vcc, 0, v2
	s_cbranch_vccnz .LBB0_756
	v_readlane_b32 s2, v248, 8
	s_waitcnt lgkmcnt(0)
	v_mov_b32_e32 v0, 0
	v_readlane_b32 s3, v248, 9
	s_nop 4
	global_load_dword v1, v0, s[2:3] offset:18
	global_load_ushort v2, v0, s[2:3] offset:22
	s_mov_b32 s47, 1
	s_waitcnt vmcnt(1)
	v_cmp_ne_u32_sdwa s[2:3], v1, v0 src0_sel:WORD_0 src1_sel:DWORD
	s_cmp_lg_u64 s[2:3], 0
	v_readlane_b32 s2, v248, 10
	v_cmp_ne_u32_sdwa s[4:5], v1, v0 src0_sel:WORD_1 src1_sel:DWORD
	s_addc_u32 s2, s2, 0
	v_readlane_b32 s3, v248, 11
	s_cmp_lg_u64 s[4:5], 0
	s_waitcnt vmcnt(0)
	v_cmp_ne_u32_e32 vcc, 0, v2
	s_addc_u32 s3, s3, 0
	s_mul_i32 s46, s3, s2
	s_cmp_lg_u64 vcc, 0
	v_readlane_b32 s2, v248, 12
	s_addc_u32 s2, s2, 0
	s_mul_i32 s46, s46, s2
	s_add_u32 s2, s58, 0x3e680200
	s_addc_u32 s3, s59, 0
	s_add_u32 s4, s58, 0x3e680400
	s_addc_u32 s5, s59, 0
	s_add_u32 s6, s58, 0x3e680500
	s_addc_u32 s7, s59, 0
	s_add_u32 s8, s58, 0x3e680600
	s_addc_u32 s9, s59, 0
	s_add_u32 s12, s58, 0x3e680700
	s_addc_u32 s13, s59, 0
	s_add_u32 s14, s58, 0x3e680800
	s_addc_u32 s15, s59, 0
	s_add_u32 s16, s58, 0x3e680900
	s_addc_u32 s17, s59, 0
	s_add_u32 s18, s58, 0x3e680a00
	s_addc_u32 s19, s59, 0
	s_add_u32 s20, s58, 0x3e680b00
	s_addc_u32 s21, s59, 0
	s_add_u32 s22, s58, 0x3e680c00
	s_addc_u32 s23, s59, 0
	s_add_u32 s24, s58, 0x3e680d00
	s_addc_u32 s25, s59, 0
	s_add_u32 s26, s58, 0x3e680e00
	s_addc_u32 s27, s59, 0
	s_add_u32 s28, s58, 0x3e680f00
	s_addc_u32 s29, s59, 0
	s_add_u32 s30, s58, 0x3e681000
	s_addc_u32 s31, s59, 0
	s_add_u32 s34, s58, 0x3e681100
	s_addc_u32 s35, s59, 0
	s_add_u32 s36, s58, 0x3e681200
	s_addc_u32 s37, s59, 0
	s_add_u32 s38, s58, 0x3e681300
	s_addc_u32 s39, s59, 0
	s_branch .LBB0_744

.LBB0_814:
	s_waitcnt vmcnt(0)
	s_waitcnt vmcnt(0) lgkmcnt(0)
	s_barrier
	s_mov_b64 s[0:1], exec
	v_readlane_b32 s2, v248, 48
	v_readlane_b32 s3, v248, 49
	s_and_b64 s[2:3], s[0:1], s[2:3]
	s_mov_b64 exec, s[2:3]
	s_cbranch_execz .LBB0_866
	s_add_i32 s2, 0, 0x22000
	v_mov_b32_e32 v0, s2
	s_waitcnt vmcnt(0) expcnt(0) lgkmcnt(0)
	buffer_inv sc1
	ds_read_b32 v2, v0
	s_add_i32 s2, 0, 0x22004
	v_mov_b32_e32 v0, s2
	ds_read_b32 v0, v0
	s_waitcnt lgkmcnt(1)
	v_cmp_ne_u32_e32 vcc, 0, v2
	s_cbranch_vccnz .LBB0_830
	v_readlane_b32 s2, v248, 8
	s_waitcnt lgkmcnt(0)
	v_mov_b32_e32 v0, 0
	v_readlane_b32 s3, v248, 9
	s_nop 4
	global_load_dword v1, v0, s[2:3] offset:18
	global_load_ushort v2, v0, s[2:3] offset:22
	s_mov_b32 s49, 1
	s_waitcnt vmcnt(1)
	v_cmp_ne_u32_sdwa s[2:3], v1, v0 src0_sel:WORD_0 src1_sel:DWORD
	s_cmp_lg_u64 s[2:3], 0
	v_readlane_b32 s2, v248, 10
	v_cmp_ne_u32_sdwa s[4:5], v1, v0 src0_sel:WORD_1 src1_sel:DWORD
	s_addc_u32 s2, s2, 0
	v_readlane_b32 s3, v248, 11
	s_cmp_lg_u64 s[4:5], 0
	s_waitcnt vmcnt(0)
	v_cmp_ne_u32_e32 vcc, 0, v2
	s_addc_u32 s3, s3, 0
	s_mul_i32 s48, s3, s2
	s_cmp_lg_u64 vcc, 0
	v_readlane_b32 s2, v248, 12
	s_addc_u32 s2, s2, 0
	s_mul_i32 s48, s48, s2
	s_add_u32 s2, s58, 0x3e680200
	s_addc_u32 s3, s59, 0
	s_add_u32 s4, s58, 0x3e680400
	s_addc_u32 s5, s59, 0
	s_add_u32 s6, s58, 0x3e680500
	s_addc_u32 s7, s59, 0
	s_add_u32 s8, s58, 0x3e680600
	s_addc_u32 s9, s59, 0
	s_add_u32 s14, s58, 0x3e680700
	s_addc_u32 s15, s59, 0
	s_add_u32 s16, s58, 0x3e680800
	s_addc_u32 s17, s59, 0
	s_add_u32 s18, s58, 0x3e680900
	s_addc_u32 s19, s59, 0
	s_add_u32 s20, s58, 0x3e680a00
	s_addc_u32 s21, s59, 0
	s_add_u32 s22, s58, 0x3e680b00
	s_addc_u32 s23, s59, 0
	s_add_u32 s24, s58, 0x3e680c00
	s_addc_u32 s25, s59, 0
	s_add_u32 s26, s58, 0x3e680d00
	s_addc_u32 s27, s59, 0
	s_add_u32 s28, s58, 0x3e680e00
	s_addc_u32 s29, s59, 0
	s_add_u32 s30, s58, 0x3e680f00
	s_addc_u32 s31, s59, 0
	s_add_u32 s34, s58, 0x3e681000
	s_addc_u32 s35, s59, 0
	s_add_u32 s36, s58, 0x3e681100
	s_addc_u32 s37, s59, 0
	s_add_u32 s38, s58, 0x3e681200
	s_addc_u32 s39, s59, 0
	s_add_u32 s40, s58, 0x3e681300
	s_addc_u32 s41, s59, 0
	s_branch .LBB0_818

.LBB0_901:
	s_or_b64 exec, exec, s[2:3]
	s_waitcnt vmcnt(0)
	s_barrier
	s_mov_b64 s[0:1], exec
	v_readlane_b32 s2, v248, 48
	v_readlane_b32 s3, v248, 49
	s_and_b64 s[2:3], s[0:1], s[2:3]
	s_mov_b64 exec, s[2:3]
	s_cbranch_execz .LBB0_953
	s_add_i32 s2, 0, 0x22000
	v_mov_b32_e32 v0, s2
	s_waitcnt vmcnt(0) expcnt(0) lgkmcnt(0)
	buffer_inv sc1
	ds_read_b32 v2, v0
	s_add_i32 s2, 0, 0x22004
	v_mov_b32_e32 v0, s2
	ds_read_b32 v0, v0
	s_waitcnt lgkmcnt(1)
	v_cmp_ne_u32_e32 vcc, 0, v2
	s_cbranch_vccnz .LBB0_917
	v_readlane_b32 s2, v248, 8
	s_waitcnt lgkmcnt(0)
	v_mov_b32_e32 v0, 0
	v_readlane_b32 s3, v248, 9
	s_nop 4
	global_load_dword v1, v0, s[2:3] offset:18
	global_load_ushort v2, v0, s[2:3] offset:22
	s_mov_b32 s45, 1
	s_waitcnt vmcnt(1)
	v_cmp_ne_u32_sdwa s[2:3], v1, v0 src0_sel:WORD_0 src1_sel:DWORD
	s_cmp_lg_u64 s[2:3], 0
	v_readlane_b32 s2, v248, 10
	v_cmp_ne_u32_sdwa s[4:5], v1, v0 src0_sel:WORD_1 src1_sel:DWORD
	s_addc_u32 s2, s2, 0
	v_readlane_b32 s3, v248, 11
	s_cmp_lg_u64 s[4:5], 0
	s_waitcnt vmcnt(0)
	v_cmp_ne_u32_e32 vcc, 0, v2
	s_addc_u32 s3, s3, 0
	s_mul_i32 s44, s3, s2
	s_cmp_lg_u64 vcc, 0
	v_readlane_b32 s2, v248, 12
	s_addc_u32 s2, s2, 0
	s_mul_i32 s44, s44, s2
	s_add_u32 s2, s58, 0x3e680200
	s_addc_u32 s3, s59, 0
	s_add_u32 s4, s58, 0x3e680400
	s_addc_u32 s5, s59, 0
	s_add_u32 s6, s58, 0x3e680500
	s_addc_u32 s7, s59, 0
	s_add_u32 s8, s58, 0x3e680600
	s_addc_u32 s9, s59, 0
	s_add_u32 s10, s58, 0x3e680700
	s_addc_u32 s11, s59, 0
	s_add_u32 s12, s58, 0x3e680800
	s_addc_u32 s13, s59, 0
	s_add_u32 s14, s58, 0x3e680900
	s_addc_u32 s15, s59, 0
	s_add_u32 s16, s58, 0x3e680a00
	s_addc_u32 s17, s59, 0
	s_add_u32 s18, s58, 0x3e680b00
	s_addc_u32 s19, s59, 0
	s_add_u32 s20, s58, 0x3e680c00
	s_addc_u32 s21, s59, 0
	s_add_u32 s22, s58, 0x3e680d00
	s_addc_u32 s23, s59, 0
	s_add_u32 s24, s58, 0x3e680e00
	s_addc_u32 s25, s59, 0
	s_add_u32 s26, s58, 0x3e680f00
	s_addc_u32 s27, s59, 0
	s_add_u32 s28, s58, 0x3e681000
	s_addc_u32 s29, s59, 0
	s_add_u32 s30, s58, 0x3e681100
	s_addc_u32 s31, s59, 0
	s_add_u32 s34, s58, 0x3e681200
	s_addc_u32 s35, s59, 0
	s_add_u32 s36, s58, 0x3e681300
	s_addc_u32 s37, s59, 0
	s_branch .LBB0_905

.LBB0_957:
	v_readlane_b32 s0, v247, 19
	v_readlane_b32 s1, v247, 20
	s_or_b64 exec, exec, s[0:1]
	s_waitcnt vmcnt(0)
	s_barrier
	s_mov_b64 s[0:1], exec
	v_readlane_b32 s2, v248, 48
	v_readlane_b32 s3, v248, 49
	s_and_b64 s[2:3], s[0:1], s[2:3]
	s_mov_b64 exec, s[2:3]
	s_cbranch_execz .LBB0_1009
	s_add_i32 s2, 0, 0x22000
	v_mov_b32_e32 v0, s2
	s_waitcnt vmcnt(0) expcnt(0) lgkmcnt(0)
	buffer_inv sc1
	ds_read_b32 v2, v0
	s_add_i32 s2, 0, 0x22004
	v_mov_b32_e32 v0, s2
	ds_read_b32 v0, v0
	s_waitcnt lgkmcnt(1)
	v_cmp_ne_u32_e32 vcc, 0, v2
	s_cbranch_vccnz .LBB0_973
	v_readlane_b32 s2, v248, 8
	s_waitcnt lgkmcnt(0)
	v_mov_b32_e32 v0, 0
	v_readlane_b32 s3, v248, 9
	s_nop 4
	global_load_dword v1, v0, s[2:3] offset:18
	global_load_ushort v2, v0, s[2:3] offset:22
	s_mov_b32 s45, 1
	s_waitcnt vmcnt(1)
	v_cmp_ne_u32_sdwa s[2:3], v1, v0 src0_sel:WORD_0 src1_sel:DWORD
	s_cmp_lg_u64 s[2:3], 0
	v_readlane_b32 s2, v248, 10
	v_cmp_ne_u32_sdwa s[4:5], v1, v0 src0_sel:WORD_1 src1_sel:DWORD
	s_addc_u32 s2, s2, 0
	v_readlane_b32 s3, v248, 11
	s_cmp_lg_u64 s[4:5], 0
	s_waitcnt vmcnt(0)
	v_cmp_ne_u32_e32 vcc, 0, v2
	s_addc_u32 s3, s3, 0
	s_mul_i32 s44, s3, s2
	s_cmp_lg_u64 vcc, 0
	v_readlane_b32 s2, v248, 12
	s_addc_u32 s2, s2, 0
	s_mul_i32 s44, s44, s2
	s_add_u32 s2, s58, 0x3e680200
	s_addc_u32 s3, s59, 0
	s_add_u32 s4, s58, 0x3e680400
	s_addc_u32 s5, s59, 0
	s_add_u32 s6, s58, 0x3e680500
	s_addc_u32 s7, s59, 0
	s_add_u32 s8, s58, 0x3e680600
	s_addc_u32 s9, s59, 0
	s_add_u32 s10, s58, 0x3e680700
	s_addc_u32 s11, s59, 0
	s_add_u32 s12, s58, 0x3e680800
	s_addc_u32 s13, s59, 0
	s_add_u32 s14, s58, 0x3e680900
	s_addc_u32 s15, s59, 0
	s_add_u32 s16, s58, 0x3e680a00
	s_addc_u32 s17, s59, 0
	s_add_u32 s18, s58, 0x3e680b00
	s_addc_u32 s19, s59, 0
	s_add_u32 s20, s58, 0x3e680c00
	s_addc_u32 s21, s59, 0
	s_add_u32 s22, s58, 0x3e680d00
	s_addc_u32 s23, s59, 0
	s_add_u32 s24, s58, 0x3e680e00
	s_addc_u32 s25, s59, 0
	s_add_u32 s26, s58, 0x3e680f00
	s_addc_u32 s27, s59, 0
	s_add_u32 s28, s58, 0x3e681000
	s_addc_u32 s29, s59, 0
	s_add_u32 s30, s58, 0x3e681100
	s_addc_u32 s31, s59, 0
	s_add_u32 s34, s58, 0x3e681200
	s_addc_u32 s35, s59, 0
	s_add_u32 s36, s58, 0x3e681300
	s_addc_u32 s37, s59, 0
	s_branch .LBB0_961

.LBB0_1347:
	s_waitcnt vmcnt(0)
	s_barrier
	s_mov_b64 s[0:1], exec
	v_readlane_b32 s2, v248, 48
	v_readlane_b32 s3, v248, 49
	s_and_b64 s[2:3], s[0:1], s[2:3]
	s_mov_b64 exec, s[2:3]
	s_cbranch_execz .LBB0_1399
	s_add_i32 s2, 0, 0x22000
	v_mov_b32_e32 v0, s2
	s_waitcnt vmcnt(0) expcnt(0) lgkmcnt(0)
	buffer_inv sc1
	ds_read_b32 v2, v0
	s_add_i32 s2, 0, 0x22004
	v_mov_b32_e32 v0, s2
	ds_read_b32 v0, v0
	s_waitcnt lgkmcnt(1)
	v_cmp_ne_u32_e32 vcc, 0, v2
	s_cbranch_vccnz .LBB0_1363
	v_readlane_b32 s2, v248, 8
	s_waitcnt lgkmcnt(0)
	v_mov_b32_e32 v0, 0
	v_readlane_b32 s3, v248, 9
	s_nop 4
	global_load_dword v1, v0, s[2:3] offset:18
	global_load_ushort v2, v0, s[2:3] offset:22
	s_mov_b32 s45, 1
	s_waitcnt vmcnt(1)
	v_cmp_ne_u32_sdwa s[2:3], v1, v0 src0_sel:WORD_0 src1_sel:DWORD
	s_cmp_lg_u64 s[2:3], 0
	v_readlane_b32 s2, v248, 10
	v_cmp_ne_u32_sdwa s[4:5], v1, v0 src0_sel:WORD_1 src1_sel:DWORD
	s_addc_u32 s2, s2, 0
	v_readlane_b32 s3, v248, 11
	s_cmp_lg_u64 s[4:5], 0
	s_waitcnt vmcnt(0)
	v_cmp_ne_u32_e32 vcc, 0, v2
	s_addc_u32 s3, s3, 0
	s_mul_i32 s44, s3, s2
	s_cmp_lg_u64 vcc, 0
	v_readlane_b32 s2, v248, 12
	s_addc_u32 s2, s2, 0
	s_mul_i32 s44, s44, s2
	s_add_u32 s2, s58, 0x3e680200
	s_addc_u32 s3, s59, 0
	s_add_u32 s4, s58, 0x3e680400
	s_addc_u32 s5, s59, 0
	s_add_u32 s6, s58, 0x3e680500
	s_addc_u32 s7, s59, 0
	s_add_u32 s8, s58, 0x3e680600
	s_addc_u32 s9, s59, 0
	s_add_u32 s10, s58, 0x3e680700
	s_addc_u32 s11, s59, 0
	s_add_u32 s12, s58, 0x3e680800
	s_addc_u32 s13, s59, 0
	s_add_u32 s14, s58, 0x3e680900
	s_addc_u32 s15, s59, 0
	s_add_u32 s16, s58, 0x3e680a00
	s_addc_u32 s17, s59, 0
	s_add_u32 s18, s58, 0x3e680b00
	s_addc_u32 s19, s59, 0
	s_add_u32 s20, s58, 0x3e680c00
	s_addc_u32 s21, s59, 0
	s_add_u32 s22, s58, 0x3e680d00
	s_addc_u32 s23, s59, 0
	s_add_u32 s24, s58, 0x3e680e00
	s_addc_u32 s25, s59, 0
	s_add_u32 s26, s58, 0x3e680f00
	s_addc_u32 s27, s59, 0
	s_add_u32 s28, s58, 0x3e681000
	s_addc_u32 s29, s59, 0
	s_add_u32 s30, s58, 0x3e681100
	s_addc_u32 s31, s59, 0
	s_add_u32 s34, s58, 0x3e681200
	s_addc_u32 s35, s59, 0
	s_add_u32 s36, s58, 0x3e681300
	s_addc_u32 s37, s59, 0
	s_branch .LBB0_1351

.LBB0_1413:
	s_waitcnt vmcnt(0)
	s_waitcnt vmcnt(0) lgkmcnt(0)
	s_barrier
	s_mov_b64 s[0:1], exec
	v_readlane_b32 s2, v248, 48
	v_readlane_b32 s3, v248, 49
	s_and_b64 s[2:3], s[0:1], s[2:3]
	s_mov_b64 exec, s[2:3]
	s_cbranch_execz .LBB0_1465
	s_add_i32 s2, 0, 0x22000
	v_mov_b32_e32 v0, s2
	s_waitcnt vmcnt(0) expcnt(0) lgkmcnt(0)
	buffer_inv sc1
	ds_read_b32 v2, v0
	s_add_i32 s2, 0, 0x22004
	v_mov_b32_e32 v0, s2
	ds_read_b32 v0, v0
	s_waitcnt lgkmcnt(1)
	v_cmp_ne_u32_e32 vcc, 0, v2
	s_cbranch_vccnz .LBB0_1429
	v_readlane_b32 s2, v248, 8
	s_waitcnt lgkmcnt(0)
	v_mov_b32_e32 v0, 0
	v_readlane_b32 s3, v248, 9
	s_nop 4
	global_load_dword v1, v0, s[2:3] offset:18
	global_load_ushort v2, v0, s[2:3] offset:22
	s_mov_b32 s45, 1
	s_waitcnt vmcnt(1)
	v_cmp_ne_u32_sdwa s[2:3], v1, v0 src0_sel:WORD_0 src1_sel:DWORD
	s_cmp_lg_u64 s[2:3], 0
	v_readlane_b32 s2, v248, 10
	v_cmp_ne_u32_sdwa s[4:5], v1, v0 src0_sel:WORD_1 src1_sel:DWORD
	s_addc_u32 s2, s2, 0
	v_readlane_b32 s3, v248, 11
	s_cmp_lg_u64 s[4:5], 0
	s_waitcnt vmcnt(0)
	v_cmp_ne_u32_e32 vcc, 0, v2
	s_addc_u32 s3, s3, 0
	s_mul_i32 s44, s3, s2
	s_cmp_lg_u64 vcc, 0
	v_readlane_b32 s2, v248, 12
	s_addc_u32 s2, s2, 0
	s_mul_i32 s44, s44, s2
	s_add_u32 s2, s58, 0x3e680200
	s_addc_u32 s3, s59, 0
	s_add_u32 s4, s58, 0x3e680400
	s_addc_u32 s5, s59, 0
	s_add_u32 s6, s58, 0x3e680500
	s_addc_u32 s7, s59, 0
	s_add_u32 s8, s58, 0x3e680600
	s_addc_u32 s9, s59, 0
	s_add_u32 s10, s58, 0x3e680700
	s_addc_u32 s11, s59, 0
	s_add_u32 s12, s58, 0x3e680800
	s_addc_u32 s13, s59, 0
	s_add_u32 s14, s58, 0x3e680900
	s_addc_u32 s15, s59, 0
	s_add_u32 s16, s58, 0x3e680a00
	s_addc_u32 s17, s59, 0
	s_add_u32 s18, s58, 0x3e680b00
	s_addc_u32 s19, s59, 0
	s_add_u32 s20, s58, 0x3e680c00
	s_addc_u32 s21, s59, 0
	s_add_u32 s22, s58, 0x3e680d00
	s_addc_u32 s23, s59, 0
	s_add_u32 s24, s58, 0x3e680e00
	s_addc_u32 s25, s59, 0
	s_add_u32 s26, s58, 0x3e680f00
	s_addc_u32 s27, s59, 0
	s_add_u32 s28, s58, 0x3e681000
	s_addc_u32 s29, s59, 0
	s_add_u32 s30, s58, 0x3e681100
	s_addc_u32 s31, s59, 0
	s_add_u32 s34, s58, 0x3e681200
	s_addc_u32 s35, s59, 0
	s_add_u32 s36, s58, 0x3e681300
	s_addc_u32 s37, s59, 0
	s_branch .LBB0_1417

.LBB0_1635:
	s_waitcnt vmcnt(0)
	s_waitcnt vmcnt(0) lgkmcnt(0)
	s_barrier
	s_mov_b64 s[0:1], exec
	v_readlane_b32 s2, v248, 48
	v_readlane_b32 s3, v248, 49
	s_and_b64 s[2:3], s[0:1], s[2:3]
	s_mov_b64 exec, s[2:3]
	s_cbranch_execz .LBB0_1687
	s_add_i32 s2, 0, 0x22000
	v_mov_b32_e32 v0, s2
	s_waitcnt vmcnt(0) expcnt(0) lgkmcnt(0)
	buffer_inv sc1
	ds_read_b32 v2, v0
	s_add_i32 s2, 0, 0x22004
	v_mov_b32_e32 v0, s2
	ds_read_b32 v0, v0
	s_waitcnt lgkmcnt(1)
	v_cmp_ne_u32_e32 vcc, 0, v2
	s_cbranch_vccnz .LBB0_1651
	v_readlane_b32 s2, v248, 8
	s_waitcnt lgkmcnt(0)
	v_mov_b32_e32 v0, 0
	v_readlane_b32 s3, v248, 9
	s_nop 4
	global_load_dword v1, v0, s[2:3] offset:18
	global_load_ushort v2, v0, s[2:3] offset:22
	s_mov_b32 s44, 1
	s_waitcnt vmcnt(1)
	v_cmp_ne_u32_sdwa s[2:3], v1, v0 src0_sel:WORD_0 src1_sel:DWORD
	s_cmp_lg_u64 s[2:3], 0
	v_readlane_b32 s2, v248, 10
	v_cmp_ne_u32_sdwa s[4:5], v1, v0 src0_sel:WORD_1 src1_sel:DWORD
	s_addc_u32 s2, s2, 0
	v_readlane_b32 s3, v248, 11
	s_cmp_lg_u64 s[4:5], 0
	s_waitcnt vmcnt(0)
	v_cmp_ne_u32_e32 vcc, 0, v2
	s_addc_u32 s3, s3, 0
	s_mul_i32 s33, s3, s2
	s_cmp_lg_u64 vcc, 0
	v_readlane_b32 s2, v248, 12
	s_addc_u32 s2, s2, 0
	s_mul_i32 s33, s33, s2
	s_add_u32 s2, s58, 0x3e680200
	s_addc_u32 s3, s59, 0
	s_add_u32 s4, s58, 0x3e680400
	s_addc_u32 s5, s59, 0
	s_add_u32 s6, s58, 0x3e680500
	s_addc_u32 s7, s59, 0
	s_add_u32 s8, s58, 0x3e680600
	s_addc_u32 s9, s59, 0
	s_add_u32 s10, s58, 0x3e680700
	s_addc_u32 s11, s59, 0
	s_add_u32 s12, s58, 0x3e680800
	s_addc_u32 s13, s59, 0
	s_add_u32 s14, s58, 0x3e680900
	s_addc_u32 s15, s59, 0
	s_add_u32 s16, s58, 0x3e680a00
	s_addc_u32 s17, s59, 0
	s_add_u32 s18, s58, 0x3e680b00
	s_addc_u32 s19, s59, 0
	s_add_u32 s20, s58, 0x3e680c00
	s_addc_u32 s21, s59, 0
	s_add_u32 s22, s58, 0x3e680d00
	s_addc_u32 s23, s59, 0
	s_add_u32 s24, s58, 0x3e680e00
	s_addc_u32 s25, s59, 0
	s_add_u32 s26, s58, 0x3e680f00
	s_addc_u32 s27, s59, 0
	s_add_u32 s28, s58, 0x3e681000
	s_addc_u32 s29, s59, 0
	s_add_u32 s30, s58, 0x3e681100
	s_addc_u32 s31, s59, 0
	s_add_u32 s34, s58, 0x3e681200
	s_addc_u32 s35, s59, 0
	s_add_u32 s36, s58, 0x3e681300
	s_addc_u32 s37, s59, 0
	s_branch .LBB0_1639
